# work removal stack: B-fragment LDS read addresses pre-biased (no v_add per K-tile) in UP/WIN loops + attention step trims + selected-block back edge shortened
# baseline (speedup 1.0000x reference)
.LBB0_397:
	v_readlane_b32 s56, v255, 9
	v_readlane_b32 s57, v255, 10
	s_add_u32 s4, s56, 0x5400000
	s_addc_u32 s5, s57, 0
	s_add_u32 s10, s56, 0x5600000
	s_addc_u32 s11, s57, 0
	s_add_u32 s18, s56, 0x5800000
	s_addc_u32 s19, s57, 0
	s_add_u32 s20, s56, 0x5a00000
	s_addc_u32 s21, s57, 0
	s_add_u32 s22, s56, 0x5c00000
	s_addc_u32 s23, s57, 0
	s_add_u32 s38, s56, 0x5c80000
	s_addc_u32 s39, s57, 0
	s_add_u32 s40, s56, 0x5d00000
	s_addc_u32 s41, s57, 0
	s_add_u32 s42, s56, 0x5d80000
	s_addc_u32 s43, s57, 0
	s_add_u32 s44, s56, 0x5e00000
	s_addc_u32 s45, s57, 0
	s_add_u32 s46, s56, 0x5e80000
	s_addc_u32 s47, s57, 0
	s_add_u32 s48, s56, 0x5f00000
	s_addc_u32 s49, s57, 0
	s_add_u32 s50, s56, 0x6300000
	s_addc_u32 s51, s57, 0
	v_bfe_u32 v16, v231, 4, 2
	s_add_u32 s52, s56, 0x6700000
	v_and_b32_e32 v97, 15, v231
	v_lshlrev_b32_e32 v0, 4, v16
	v_lshlrev_b32_e32 v18, 2, v231
	s_addc_u32 s53, s57, 0
	s_and_b32 s37, s36, 3
	s_lshl_b32 s28, s29, 6
	v_lshl_or_b32 v17, v97, 6, v0
	s_lshl_b32 s29, s29, 13
	v_and_b32_e32 v18, 32, v18
	s_add_i32 m0, s9, 0x18000
	v_lshl_add_u64 v[8:9], v[8:9], 0, s[34:35]
	v_bitop3_b32 v19, v17, s29, v18 bitop3:0xde
	s_lshl_b32 s29, s37, 5
	s_lshl_b32 s30, s37, 12
	s_waitcnt vmcnt(2)
	s_barrier
	global_load_lds_dwordx4 v[8:9], off
	v_lshl_add_u64 v[6:7], v[6:7], 0, s[34:35]
	s_add_i32 m0, s9, 0x1a000
	s_add_i32 s33, s9, 0x8000
	s_add_i32 s80, s9, 0xa000
	v_bitop3_b32 v169, s30, v17, v18 bitop3:0xf6
	v_add_u32_e32 v250, 0x10000, v169
	global_load_lds_dwordx4 v[6:7], off
	v_lshl_add_u64 v[2:3], v[2:3], 0, s[34:35]
	s_mov_b32 m0, s33
	s_add_u32 s30, s64, 0x40080
	global_load_lds_dwordx4 v[2:3], off
	v_lshl_add_u64 v[2:3], v[4:5], 0, s[34:35]
	s_mov_b32 m0, s80
	s_addc_u32 s31, s65, 0
	global_load_lds_dwordx4 v[2:3], off
	s_add_i32 m0, s9, 0x1c000
	v_lshl_add_u64 v[2:3], s[30:31], 0, v[166:167]
	global_load_lds_dwordx4 v[2:3], off
	v_lshl_add_u64 v[2:3], s[30:31], 0, v[94:95]
	s_add_i32 m0, s9, 0x1e000
	s_cmpk_lt_u32 s6, 0x100
	global_load_lds_dwordx4 v[2:3], off
	s_cselect_b64 s[30:31], -1, 0
	s_bfe_u32 s81, s36, 0x10001
	s_bfe_u32 s6, s6, 0x10006
	s_cmp_eq_u32 s37, 0
	v_lshlrev_b32_e32 v2, 14, v16
	v_readlane_b32 s36, v255, 15
	s_cselect_b64 s[54:55], -1, 0
	v_lshl_or_b32 v172, s6, 17, v2
	s_lshl_b32 s83, s6, 5
	s_lshl_b32 s84, s6, 4
	s_ashr_i32 s85, s36, 31
	s_lshl_b32 s6, s6, 6
	v_readlane_b32 s37, v255, 16
	s_add_u32 s36, s56, s6
	s_addc_u32 s37, s57, 0
	v_lshl_add_u64 v[2:3], s[36:37], 0, v[0:1]
	s_mov_b64 s[36:37], 0x100000
	v_lshlrev_b32_e32 v0, 14, v10
	v_lshl_add_u64 v[174:175], v[2:3], 0, s[36:37]
	s_mov_b64 s[36:37], 0x140000
	v_and_b32_e32 v0, 0xffff8000, v0
	v_lshl_add_u64 v[176:177], v[2:3], 0, s[36:37]
	v_lshl_add_u32 v0, v11, 11, v0
	v_and_b32_e32 v2, 1, v10
	v_lshl_or_b32 v0, v2, 6, v0
	v_lshl_add_u32 v178, v12, 1, v0
	v_lshlrev_b32_e32 v0, 14, v13
	v_and_b32_e32 v0, 0xffff8000, v0
	s_waitcnt vmcnt(6)
	v_lshl_add_u32 v0, v14, 11, v0
	v_and_b32_e32 v2, 1, v13
	v_lshl_or_b32 v0, v2, 6, v0
	v_readlane_b32 s36, v254, 25
	v_lshlrev_b32_e32 v168, 3, v16
	s_mov_b32 s82, 0
	v_lshlrev_b32_e32 v170, 2, v16
	v_mov_b32_e32 v173, v1
	v_mov_b32_e32 v179, v1
	v_lshl_add_u32 v180, v15, 1, v0
	v_mov_b32_e32 v181, v1
	v_add_u32_e32 v171, 0, v19
	v_readlane_b32 s78, v254, 18
	s_mov_b32 s6, s36
	s_barrier
	v_readlane_b32 s37, v254, 26
	s_branch .LBB0_400

.LBB0_402:
	s_cmp_eq_u32 s56, 4
	s_cselect_b32 s60, 19, s56
	s_cmp_eq_u32 s56, 5
	s_cselect_b32 s60, 4, s60
	s_cmp_eq_u32 s56, 10
	s_cselect_b32 s60, 5, s60
	s_cmp_eq_u32 s56, 19
	s_cselect_b32 s56, 10, s60
	s_ashr_i32 s59, s58, 31
	s_lshl_b64 s[60:61], s[58:59], 19
	s_add_u32 s60, s14, s60
	s_addc_u32 s61, s15, s61
	s_and_b64 s[62:63], s[36:37], exec
	s_cselect_b32 s59, s61, s67
	s_cselect_b32 s70, s60, s66
	s_ashr_i32 s57, s56, 31
	s_lshl_b64 s[62:63], s[56:57], 19
	s_add_u32 s62, s2, s62
	s_addc_u32 s63, s3, s63
	s_and_b64 s[68:69], s[36:37], exec
	s_cselect_b32 s57, s63, s65
	s_cselect_b32 s71, s62, s64
	s_add_u32 s72, s64, 0x100
	s_addc_u32 s73, s65, 0
	s_add_u32 s64, s66, 0x40080
	s_addc_u32 s65, s67, 0
	s_mov_b32 s74, -2
	s_cmp_eq_u32 s78, 19
	s_cselect_b32 vcc_hi, 1, 0
	v_readlane_b32 vcc_lo, v252, 19
	s_and_b32 vcc_lo, vcc_lo, 0xc0
	s_cmp_lg_u32 vcc_lo, 0
	s_cselect_b32 vcc_lo, vcc_hi, 0
	s_add_u32 s66, s64, 0xfffc0080
	s_addc_u32 s67, s65, -1
	s_add_i32 s75, 0, 0x10000
	s_cmp_eq_u32 s74, 12
	s_cselect_b32 s69, s59, s67
	s_cselect_b32 s68, s70, s66
	s_cselect_b32 s67, s57, s73
	s_cselect_b32 s66, s71, s72
	s_add_i32 s79, 0, 0x14000
	ds_read_b128 v[134:137], v250
	ds_read_b128 v[138:141], v250 offset:1024
	ds_read_b128 v[142:145], v250 offset:2048
	ds_read_b128 v[146:149], v250 offset:3072
	ds_read_b128 v[150:153], v250 offset:16384
	ds_read_b128 v[154:157], v250 offset:17408
	ds_read_b128 v[158:161], v250 offset:18432
	ds_read_b128 v[162:165], v250 offset:19456
	s_add_i32 m0, s9, 0xc000
	ds_read_b128 v[182:185], v171
	ds_read_b128 v[186:189], v171 offset:1024
	ds_read_b128 v[190:193], v171 offset:2048
	ds_read_b128 v[194:197], v171 offset:3072
	ds_read_b128 v[208:211], v171 offset:4096
	ds_read_b128 v[212:215], v171 offset:5120
	ds_read_b128 v[216:219], v171 offset:6144
	ds_read_b128 v[232:235], v171 offset:7168
	global_load_lds_dwordx4 v180, s[64:65]
	s_add_i32 m0, s9, 0xe000
	s_nop 0
	global_load_lds_dwordx4 v178, s[64:65]
	s_waitcnt vmcnt(8)
	s_waitcnt lgkmcnt(0)
	s_barrier
	s_setprio 1
	s_waitcnt lgkmcnt(0)
	s_cmp_lg_u32 vcc_lo, 0
	s_cbranch_scc1 .Lwinskip_0_pl
	v_mfma_f32_16x16x32_bf16 v[130:133], v[134:137], v[182:185], 0
	v_mfma_f32_16x16x32_bf16 v[126:129], v[142:145], v[182:185], 0
	v_mfma_f32_16x16x32_bf16 v[122:125], v[134:137], v[190:193], 0
	v_mfma_f32_16x16x32_bf16 v[118:121], v[142:145], v[190:193], 0
	v_mfma_f32_16x16x32_bf16 v[114:117], v[134:137], v[208:211], 0
	v_mfma_f32_16x16x32_bf16 v[110:113], v[142:145], v[208:211], 0
	v_mfma_f32_16x16x32_bf16 v[106:109], v[134:137], v[216:219], 0
	v_mfma_f32_16x16x32_bf16 v[102:105], v[142:145], v[216:219], 0
	v_mfma_f32_16x16x32_bf16 v[130:133], v[138:141], v[186:189], v[130:133]
	v_mfma_f32_16x16x32_bf16 v[126:129], v[146:149], v[186:189], v[126:129]
	v_mfma_f32_16x16x32_bf16 v[122:125], v[138:141], v[194:197], v[122:125]
	v_mfma_f32_16x16x32_bf16 v[118:121], v[146:149], v[194:197], v[118:121]
	v_mfma_f32_16x16x32_bf16 v[114:117], v[138:141], v[212:215], v[114:117]
	v_mfma_f32_16x16x32_bf16 v[110:113], v[146:149], v[212:215], v[110:113]
	v_mfma_f32_16x16x32_bf16 v[106:109], v[138:141], v[232:235], v[106:109]
	v_mfma_f32_16x16x32_bf16 v[102:105], v[146:149], v[232:235], v[102:105]

.Lwinskip_3_pl:
	s_setprio 0
	s_barrier
	s_add_i32 s75, 0, 0x18000
	s_add_i32 s76, 0, 0x1c000
	ds_read_b128 v[134:137], v250 offset:32768
	ds_read_b128 v[138:141], v250 offset:33792
	ds_read_b128 v[142:145], v250 offset:34816
	ds_read_b128 v[146:149], v250 offset:35840
	ds_read_b128 v[150:153], v250 offset:49152
	ds_read_b128 v[154:157], v250 offset:50176
	ds_read_b128 v[158:161], v250 offset:51200
	ds_read_b128 v[162:165], v250 offset:52224
	s_add_u32 s68, s68, 0x40000
	s_addc_u32 s69, s69, 0
	s_mov_b32 m0, s13
	ds_read_b128 v[182:185], v171 offset:32768
	ds_read_b128 v[186:189], v171 offset:33792
	ds_read_b128 v[190:193], v171 offset:34816
	ds_read_b128 v[194:197], v171 offset:35840
	ds_read_b128 v[208:211], v171 offset:36864
	ds_read_b128 v[212:215], v171 offset:37888
	ds_read_b128 v[216:219], v171 offset:38912
	ds_read_b128 v[232:235], v171 offset:39936
	global_load_lds_dwordx4 v166, s[68:69]
	s_mov_b32 m0, s25
	s_nop 0
	global_load_lds_dwordx4 v94, s[68:69]
	s_waitcnt vmcnt(8)
	s_waitcnt lgkmcnt(0)
	s_barrier
	s_setprio 1
	s_waitcnt lgkmcnt(0)
	s_cmp_lg_u32 vcc_lo, 0
	s_cbranch_scc1 .Lwinskip_4_pl
	v_mfma_f32_16x16x32_bf16 v[130:133], v[134:137], v[182:185], v[130:133]
	v_mfma_f32_16x16x32_bf16 v[126:129], v[142:145], v[182:185], v[126:129]
	v_mfma_f32_16x16x32_bf16 v[122:125], v[134:137], v[190:193], v[122:125]
	v_mfma_f32_16x16x32_bf16 v[118:121], v[142:145], v[190:193], v[118:121]
	v_mfma_f32_16x16x32_bf16 v[114:117], v[134:137], v[208:211], v[114:117]
	v_mfma_f32_16x16x32_bf16 v[110:113], v[142:145], v[208:211], v[110:113]
	v_mfma_f32_16x16x32_bf16 v[106:109], v[134:137], v[216:219], v[106:109]
	v_mfma_f32_16x16x32_bf16 v[102:105], v[142:145], v[216:219], v[102:105]
	v_mfma_f32_16x16x32_bf16 v[130:133], v[138:141], v[186:189], v[130:133]
	v_mfma_f32_16x16x32_bf16 v[126:129], v[146:149], v[186:189], v[126:129]
	v_mfma_f32_16x16x32_bf16 v[122:125], v[138:141], v[194:197], v[122:125]
	v_mfma_f32_16x16x32_bf16 v[118:121], v[146:149], v[194:197], v[118:121]
	v_mfma_f32_16x16x32_bf16 v[114:117], v[138:141], v[212:215], v[114:117]
	v_mfma_f32_16x16x32_bf16 v[110:113], v[146:149], v[212:215], v[110:113]
	v_mfma_f32_16x16x32_bf16 v[106:109], v[138:141], v[232:235], v[106:109]
	v_mfma_f32_16x16x32_bf16 v[102:105], v[146:149], v[232:235], v[102:105]

.LBB0_403:
	s_cmp_eq_u32 s78, 19
	s_cselect_b32 vcc_hi, 1, 0
	v_readlane_b32 vcc_lo, v252, 19
	s_and_b32 vcc_lo, vcc_lo, 0xc0
	s_cmp_lg_u32 vcc_lo, 0
	s_cselect_b32 vcc_lo, vcc_hi, 0
	s_add_u32 s66, s64, 0xfffc0080
	s_addc_u32 s67, s65, -1
	s_add_i32 s75, 0, 0x10000
	s_cmp_eq_u32 s74, 12
	s_cselect_b32 s69, s59, s67
	s_cselect_b32 s68, s70, s66
	s_cselect_b32 s67, s57, s73
	s_cselect_b32 s66, s71, s72
	s_add_i32 s79, 0, 0x14000
	ds_read_b128 v[134:137], v250
	ds_read_b128 v[138:141], v250 offset:1024
	ds_read_b128 v[142:145], v250 offset:2048
	ds_read_b128 v[146:149], v250 offset:3072
	ds_read_b128 v[150:153], v250 offset:16384
	ds_read_b128 v[154:157], v250 offset:17408
	ds_read_b128 v[158:161], v250 offset:18432
	ds_read_b128 v[162:165], v250 offset:19456
	s_add_i32 m0, s9, 0xc000
	ds_read_b128 v[182:185], v171
	ds_read_b128 v[186:189], v171 offset:1024
	ds_read_b128 v[190:193], v171 offset:2048
	ds_read_b128 v[194:197], v171 offset:3072
	ds_read_b128 v[208:211], v171 offset:4096
	ds_read_b128 v[212:215], v171 offset:5120
	ds_read_b128 v[216:219], v171 offset:6144
	ds_read_b128 v[232:235], v171 offset:7168
	global_load_lds_dwordx4 v180, s[64:65]
	s_add_i32 m0, s9, 0xe000
	s_nop 0
	global_load_lds_dwordx4 v178, s[64:65]
	s_waitcnt vmcnt(8)
	s_waitcnt lgkmcnt(0)
	s_barrier
	s_setprio 1
	s_waitcnt lgkmcnt(0)
	s_cmp_lg_u32 vcc_lo, 0
	s_cbranch_scc1 .Lwinskip_0
	v_mfma_f32_16x16x32_bf16 v[130:133], v[134:137], v[182:185], v[130:133]
	v_mfma_f32_16x16x32_bf16 v[126:129], v[142:145], v[182:185], v[126:129]
	v_mfma_f32_16x16x32_bf16 v[122:125], v[134:137], v[190:193], v[122:125]
	v_mfma_f32_16x16x32_bf16 v[118:121], v[142:145], v[190:193], v[118:121]
	v_mfma_f32_16x16x32_bf16 v[114:117], v[134:137], v[208:211], v[114:117]
	v_mfma_f32_16x16x32_bf16 v[110:113], v[142:145], v[208:211], v[110:113]
	v_mfma_f32_16x16x32_bf16 v[106:109], v[134:137], v[216:219], v[106:109]
	v_mfma_f32_16x16x32_bf16 v[102:105], v[142:145], v[216:219], v[102:105]
	v_mfma_f32_16x16x32_bf16 v[130:133], v[138:141], v[186:189], v[130:133]
	v_mfma_f32_16x16x32_bf16 v[126:129], v[146:149], v[186:189], v[126:129]
	v_mfma_f32_16x16x32_bf16 v[122:125], v[138:141], v[194:197], v[122:125]
	v_mfma_f32_16x16x32_bf16 v[118:121], v[146:149], v[194:197], v[118:121]
	v_mfma_f32_16x16x32_bf16 v[114:117], v[138:141], v[212:215], v[114:117]
	v_mfma_f32_16x16x32_bf16 v[110:113], v[146:149], v[212:215], v[110:113]
	v_mfma_f32_16x16x32_bf16 v[106:109], v[138:141], v[232:235], v[106:109]
	v_mfma_f32_16x16x32_bf16 v[102:105], v[146:149], v[232:235], v[102:105]

.LBB0_559:
	v_readlane_b32 s4, v255, 9
	v_readlane_b32 s5, v255, 10
	s_add_u32 s4, s4, 0x5400000
	v_lshrrev_b32_e32 v15, 1, v231
	s_addc_u32 s5, s5, 0
	v_and_b32_e32 v15, 24, v15
	s_lshl_b32 s11, s11, 5
	v_and_b32_e32 v97, 15, v231
	v_lshlrev_b32_e32 v16, 1, v15
	v_lshlrev_b32_e32 v17, 2, v231
	s_and_b32 s20, s11, 0x60
	s_add_i32 m0, s8, 0x18000
	v_lshl_add_u64 v[8:9], v[8:9], 0, s[34:35]
	s_lshl_b32 s25, s18, 6
	v_lshl_or_b32 v16, v97, 6, v16
	s_lshl_b32 s18, s18, 13
	v_and_b32_e32 v17, 32, v17
	s_lshl_b32 s11, s20, 7
	s_waitcnt vmcnt(2)
	s_barrier
	global_load_lds_dwordx4 v[8:9], off
	v_lshl_add_u64 v[6:7], v[6:7], 0, s[34:35]
	s_add_i32 m0, s8, 0x1a000
	s_add_i32 s28, s8, 0x8000
	s_add_i32 s29, s8, 0xa000
	v_bitop3_b32 v18, v16, s18, v17 bitop3:0xde
	global_load_lds_dwordx4 v[6:7], off
	v_lshl_add_u64 v[2:3], v[2:3], 0, s[34:35]
	s_mov_b32 m0, s28
	s_add_u32 s18, s38, 0x40080
	global_load_lds_dwordx4 v[2:3], off
	v_lshl_add_u64 v[2:3], v[4:5], 0, s[34:35]
	s_mov_b32 m0, s29
	s_addc_u32 s19, s39, 0
	global_load_lds_dwordx4 v[2:3], off
	s_add_i32 m0, s8, 0x1c000
	v_lshl_add_u64 v[2:3], s[18:19], 0, v[134:135]
	global_load_lds_dwordx4 v[2:3], off
	v_lshl_add_u64 v[2:3], s[18:19], 0, v[94:95]
	s_add_i32 m0, s8, 0x1e000
	v_readlane_b32 s18, v255, 15
	global_load_lds_dwordx4 v[2:3], off
	v_lshlrev_b32_e32 v2, 14, v0
	v_and_b32_e32 v2, 0xffff8000, v2
	v_lshl_add_u32 v2, v10, 11, v2
	v_and_b32_e32 v0, 1, v0
	v_lshl_or_b32 v0, v0, 6, v2
	v_lshl_add_u32 v136, v11, 1, v0
	v_lshlrev_b32_e32 v0, 14, v12
	v_and_b32_e32 v0, 0xffff8000, v0
	s_waitcnt vmcnt(6)
	s_cmpk_lt_u32 s10, 0x100
	v_readlane_b32 s19, v255, 16
	v_lshl_add_u32 v0, v13, 11, v0
	v_and_b32_e32 v2, 1, v12
	v_bitop3_b32 v141, s11, v16, v17 bitop3:0xf6
	v_add_u32_e32 v140, 0x10000, v141
	s_cselect_b64 s[10:11], -1, 0
	s_ashr_i32 s33, s18, 31
	v_lshl_or_b32 v0, v2, 6, v0
	v_readlane_b32 s18, v254, 21
	v_or_b32_e32 v143, s20, v15
	v_mov_b32_e32 v137, v1
	v_lshl_add_u32 v138, v14, 1, v0
	v_mov_b32_e32 v139, v1
	s_mov_b32 s44, 0
	v_add_u32_e32 v145, 0, v18
	v_readlane_b32 s45, v254, 15
	s_mov_b32 s46, s18
	s_barrier
	v_readlane_b32 s19, v254, 22
	s_branch .LBB0_562

.LBB0_564:
	s_ashr_i32 s21, s20, 31
	s_lshl_b64 s[22:23], s[20:21], 19
	s_add_u32 s22, s14, s22
	s_addc_u32 s23, s15, s23
	s_and_b64 s[30:31], s[36:37], exec
	s_cselect_b32 s21, s23, s41
	s_cselect_b32 s47, s22, s40
	s_ashr_i32 s19, s18, 31
	s_lshl_b64 s[30:31], s[18:19], 19
	s_add_u32 s30, s2, s30
	s_addc_u32 s31, s3, s31
	s_and_b64 s[42:43], s[36:37], exec
	s_cselect_b32 s19, s31, s39
	s_cselect_b32 s48, s30, s38
	s_add_u32 s49, s38, 0x100
	s_addc_u32 s50, s39, 0
	s_add_u32 s38, s40, 0x40080
	s_addc_u32 s39, s41, 0
	s_mov_b32 s51, -2
	s_add_u32 s40, s38, 0xfffc0080
	s_addc_u32 s41, s39, -1
	s_add_i32 s52, 0, 0x10000
	s_cmp_eq_u32 s51, 12
	s_cselect_b32 s43, s21, s41
	s_cselect_b32 s42, s47, s40
	s_cselect_b32 s41, s19, s50
	s_cselect_b32 s40, s48, s49
	s_add_i32 s54, 0, 0x14000
	ds_read_b128 v[146:149], v140
	ds_read_b128 v[150:153], v140 offset:1024
	ds_read_b128 v[154:157], v140 offset:2048
	ds_read_b128 v[158:161], v140 offset:3072
	ds_read_b128 v[162:165], v140 offset:16384
	ds_read_b128 v[166:169], v140 offset:17408
	ds_read_b128 v[170:173], v140 offset:18432
	ds_read_b128 v[174:177], v140 offset:19456
	s_add_i32 m0, s8, 0xc000
	ds_read_b128 v[178:181], v145
	ds_read_b128 v[182:185], v145 offset:1024
	ds_read_b128 v[186:189], v145 offset:2048
	ds_read_b128 v[190:193], v145 offset:3072
	ds_read_b128 v[194:197], v145 offset:4096
	ds_read_b128 v[208:211], v145 offset:5120
	ds_read_b128 v[212:215], v145 offset:6144
	ds_read_b128 v[216:219], v145 offset:7168
	global_load_lds_dwordx4 v138, s[38:39]
	s_add_i32 m0, s8, 0xe000
	s_nop 0
	global_load_lds_dwordx4 v136, s[38:39]
	s_waitcnt vmcnt(8)
	s_waitcnt lgkmcnt(0)
	s_barrier
	s_setprio 1
	s_waitcnt lgkmcnt(0)
	v_mfma_f32_16x16x32_bf16 v[130:133], v[146:149], v[178:181], 0
	v_mfma_f32_16x16x32_bf16 v[126:129], v[154:157], v[178:181], 0
	v_mfma_f32_16x16x32_bf16 v[114:117], v[146:149], v[186:189], 0
	v_mfma_f32_16x16x32_bf16 v[110:113], v[154:157], v[186:189], 0
	v_mfma_f32_16x16x32_bf16 v[98:101], v[146:149], v[194:197], 0
	v_mfma_f32_16x16x32_bf16 v[90:93], v[154:157], v[194:197], 0
	v_mfma_f32_16x16x32_bf16 v[78:81], v[146:149], v[212:215], 0
	v_mfma_f32_16x16x32_bf16 v[74:77], v[154:157], v[212:215], 0
	v_mfma_f32_16x16x32_bf16 v[130:133], v[150:153], v[182:185], v[130:133]
	v_mfma_f32_16x16x32_bf16 v[126:129], v[158:161], v[182:185], v[126:129]
	v_mfma_f32_16x16x32_bf16 v[114:117], v[150:153], v[190:193], v[114:117]
	v_mfma_f32_16x16x32_bf16 v[110:113], v[158:161], v[190:193], v[110:113]
	v_mfma_f32_16x16x32_bf16 v[98:101], v[150:153], v[208:211], v[98:101]
	v_mfma_f32_16x16x32_bf16 v[90:93], v[158:161], v[208:211], v[90:93]
	v_mfma_f32_16x16x32_bf16 v[78:81], v[150:153], v[216:219], v[78:81]
	v_mfma_f32_16x16x32_bf16 v[74:77], v[158:161], v[216:219], v[74:77]
	s_setprio 0
	s_setprio 1
	v_mfma_f32_16x16x32_bf16 v[122:125], v[162:165], v[178:181], 0
	v_mfma_f32_16x16x32_bf16 v[118:121], v[170:173], v[178:181], 0
	v_mfma_f32_16x16x32_bf16 v[106:109], v[162:165], v[186:189], 0
	v_mfma_f32_16x16x32_bf16 v[102:105], v[170:173], v[186:189], 0
	v_mfma_f32_16x16x32_bf16 v[86:89], v[162:165], v[194:197], 0
	v_mfma_f32_16x16x32_bf16 v[82:85], v[170:173], v[194:197], 0
	v_mfma_f32_16x16x32_bf16 v[70:73], v[162:165], v[212:215], 0
	v_mfma_f32_16x16x32_bf16 v[66:69], v[170:173], v[212:215], 0
	v_mfma_f32_16x16x32_bf16 v[122:125], v[166:169], v[182:185], v[122:125]
	v_mfma_f32_16x16x32_bf16 v[118:121], v[174:177], v[182:185], v[118:121]
	v_mfma_f32_16x16x32_bf16 v[106:109], v[166:169], v[190:193], v[106:109]
	v_mfma_f32_16x16x32_bf16 v[102:105], v[174:177], v[190:193], v[102:105]
	v_mfma_f32_16x16x32_bf16 v[86:89], v[166:169], v[208:211], v[86:89]
	v_mfma_f32_16x16x32_bf16 v[82:85], v[174:177], v[208:211], v[82:85]
	v_mfma_f32_16x16x32_bf16 v[70:73], v[166:169], v[216:219], v[70:73]
	v_mfma_f32_16x16x32_bf16 v[66:69], v[174:177], v[216:219], v[66:69]
	s_setprio 0
	s_barrier
	s_add_i32 s52, s52, s6
	s_mov_b32 m0, s52
	ds_read_b128 v[178:181], v145 offset:16384
	ds_read_b128 v[182:185], v145 offset:17408
	ds_read_b128 v[186:189], v145 offset:18432
	ds_read_b128 v[190:193], v145 offset:19456
	ds_read_b128 v[194:197], v145 offset:20480
	ds_read_b128 v[208:211], v145 offset:21504
	ds_read_b128 v[212:215], v145 offset:22528
	ds_read_b128 v[216:219], v145 offset:23552
	global_load_lds_dwordx4 v134, s[40:41]
	s_add_i32 m0, s52, 0x2000
	s_add_u32 s52, s40, 0x40000
	s_addc_u32 s53, s41, 0
	s_add_i32 s54, s54, s6
	global_load_lds_dwordx4 v94, s[40:41]
	s_mov_b32 m0, s54
	s_nop 0
	global_load_lds_dwordx4 v134, s[52:53]
	s_add_i32 m0, s54, 0x2000
	s_nop 0
	global_load_lds_dwordx4 v94, s[52:53]
	s_mov_b32 m0, s8
	s_nop 0
	global_load_lds_dwordx4 v134, s[42:43]
	s_mov_b32 m0, s9
	s_nop 0
	global_load_lds_dwordx4 v94, s[42:43]
	s_waitcnt vmcnt(8)
	s_waitcnt lgkmcnt(0)
	s_barrier
	s_setprio 1
	s_waitcnt lgkmcnt(0)
	v_mfma_f32_16x16x32_bf16 v[62:65], v[146:149], v[178:181], 0
	v_mfma_f32_16x16x32_bf16 v[58:61], v[154:157], v[178:181], 0
	v_mfma_f32_16x16x32_bf16 v[46:49], v[146:149], v[186:189], 0
	v_mfma_f32_16x16x32_bf16 v[42:45], v[154:157], v[186:189], 0
	v_mfma_f32_16x16x32_bf16 v[30:33], v[146:149], v[194:197], 0
	v_mfma_f32_16x16x32_bf16 v[26:29], v[154:157], v[194:197], 0
	v_mfma_f32_16x16x32_bf16 v[14:17], v[146:149], v[212:215], 0
	v_mfma_f32_16x16x32_bf16 v[10:13], v[154:157], v[212:215], 0
	v_mfma_f32_16x16x32_bf16 v[62:65], v[150:153], v[182:185], v[62:65]
	v_mfma_f32_16x16x32_bf16 v[58:61], v[158:161], v[182:185], v[58:61]
	v_mfma_f32_16x16x32_bf16 v[46:49], v[150:153], v[190:193], v[46:49]
	v_mfma_f32_16x16x32_bf16 v[42:45], v[158:161], v[190:193], v[42:45]
	v_mfma_f32_16x16x32_bf16 v[30:33], v[150:153], v[208:211], v[30:33]
	v_mfma_f32_16x16x32_bf16 v[26:29], v[158:161], v[208:211], v[26:29]
	v_mfma_f32_16x16x32_bf16 v[14:17], v[150:153], v[216:219], v[14:17]
	v_mfma_f32_16x16x32_bf16 v[10:13], v[158:161], v[216:219], v[10:13]
	s_setprio 0
	s_setprio 1
	v_mfma_f32_16x16x32_bf16 v[54:57], v[162:165], v[178:181], 0
	v_mfma_f32_16x16x32_bf16 v[50:53], v[170:173], v[178:181], 0
	v_mfma_f32_16x16x32_bf16 v[38:41], v[162:165], v[186:189], 0
	v_mfma_f32_16x16x32_bf16 v[34:37], v[170:173], v[186:189], 0
	v_mfma_f32_16x16x32_bf16 v[22:25], v[162:165], v[194:197], 0
	v_mfma_f32_16x16x32_bf16 v[18:21], v[170:173], v[194:197], 0
	v_mfma_f32_16x16x32_bf16 v[6:9], v[162:165], v[212:215], 0
	v_mfma_f32_16x16x32_bf16 v[2:5], v[170:173], v[212:215], 0
	v_mfma_f32_16x16x32_bf16 v[54:57], v[166:169], v[182:185], v[54:57]
	v_mfma_f32_16x16x32_bf16 v[50:53], v[174:177], v[182:185], v[50:53]
	v_mfma_f32_16x16x32_bf16 v[38:41], v[166:169], v[190:193], v[38:41]
	v_mfma_f32_16x16x32_bf16 v[34:37], v[174:177], v[190:193], v[34:37]
	v_mfma_f32_16x16x32_bf16 v[22:25], v[166:169], v[208:211], v[22:25]
	v_mfma_f32_16x16x32_bf16 v[18:21], v[174:177], v[208:211], v[18:21]
	v_mfma_f32_16x16x32_bf16 v[6:9], v[166:169], v[216:219], v[6:9]
	v_mfma_f32_16x16x32_bf16 v[2:5], v[174:177], v[216:219], v[2:5]
	s_setprio 0
	s_barrier
	s_add_i32 s52, 0, 0x18000
	s_add_i32 s53, 0, 0x1c000
	ds_read_b128 v[146:149], v140 offset:32768
	ds_read_b128 v[150:153], v140 offset:33792
	ds_read_b128 v[154:157], v140 offset:34816
	ds_read_b128 v[158:161], v140 offset:35840
	ds_read_b128 v[162:165], v140 offset:49152
	ds_read_b128 v[166:169], v140 offset:50176
	ds_read_b128 v[170:173], v140 offset:51200
	ds_read_b128 v[174:177], v140 offset:52224
	s_add_u32 s42, s42, 0x40000
	s_addc_u32 s43, s43, 0
	s_mov_b32 m0, s12
	ds_read_b128 v[178:181], v145 offset:32768
	ds_read_b128 v[182:185], v145 offset:33792
	ds_read_b128 v[186:189], v145 offset:34816
	ds_read_b128 v[190:193], v145 offset:35840
	ds_read_b128 v[194:197], v145 offset:36864
	ds_read_b128 v[208:211], v145 offset:37888
	ds_read_b128 v[212:215], v145 offset:38912
	ds_read_b128 v[216:219], v145 offset:39936
	global_load_lds_dwordx4 v134, s[42:43]
	s_mov_b32 m0, s13
	s_nop 0
	global_load_lds_dwordx4 v94, s[42:43]
	s_waitcnt vmcnt(8)
	s_waitcnt lgkmcnt(0)
	s_barrier
	s_setprio 1
	s_waitcnt lgkmcnt(0)
	v_mfma_f32_16x16x32_bf16 v[130:133], v[146:149], v[178:181], v[130:133]
	v_mfma_f32_16x16x32_bf16 v[126:129], v[154:157], v[178:181], v[126:129]
	v_mfma_f32_16x16x32_bf16 v[114:117], v[146:149], v[186:189], v[114:117]
	v_mfma_f32_16x16x32_bf16 v[110:113], v[154:157], v[186:189], v[110:113]
	v_mfma_f32_16x16x32_bf16 v[98:101], v[146:149], v[194:197], v[98:101]
	v_mfma_f32_16x16x32_bf16 v[90:93], v[154:157], v[194:197], v[90:93]
	v_mfma_f32_16x16x32_bf16 v[78:81], v[146:149], v[212:215], v[78:81]
	v_mfma_f32_16x16x32_bf16 v[74:77], v[154:157], v[212:215], v[74:77]
	v_mfma_f32_16x16x32_bf16 v[130:133], v[150:153], v[182:185], v[130:133]
	v_mfma_f32_16x16x32_bf16 v[126:129], v[158:161], v[182:185], v[126:129]
	v_mfma_f32_16x16x32_bf16 v[114:117], v[150:153], v[190:193], v[114:117]
	v_mfma_f32_16x16x32_bf16 v[110:113], v[158:161], v[190:193], v[110:113]
	v_mfma_f32_16x16x32_bf16 v[98:101], v[150:153], v[208:211], v[98:101]
	v_mfma_f32_16x16x32_bf16 v[90:93], v[158:161], v[208:211], v[90:93]
	v_mfma_f32_16x16x32_bf16 v[78:81], v[150:153], v[216:219], v[78:81]
	v_mfma_f32_16x16x32_bf16 v[74:77], v[158:161], v[216:219], v[74:77]
	s_setprio 0
	s_setprio 1
	v_mfma_f32_16x16x32_bf16 v[122:125], v[162:165], v[178:181], v[122:125]
	v_mfma_f32_16x16x32_bf16 v[118:121], v[170:173], v[178:181], v[118:121]
	v_mfma_f32_16x16x32_bf16 v[106:109], v[162:165], v[186:189], v[106:109]
	v_mfma_f32_16x16x32_bf16 v[102:105], v[170:173], v[186:189], v[102:105]
	v_mfma_f32_16x16x32_bf16 v[86:89], v[162:165], v[194:197], v[86:89]
	v_mfma_f32_16x16x32_bf16 v[82:85], v[170:173], v[194:197], v[82:85]
	v_mfma_f32_16x16x32_bf16 v[70:73], v[162:165], v[212:215], v[70:73]
	v_mfma_f32_16x16x32_bf16 v[66:69], v[170:173], v[212:215], v[66:69]
	v_mfma_f32_16x16x32_bf16 v[122:125], v[166:169], v[182:185], v[122:125]
	v_mfma_f32_16x16x32_bf16 v[118:121], v[174:177], v[182:185], v[118:121]
	v_mfma_f32_16x16x32_bf16 v[106:109], v[166:169], v[190:193], v[106:109]
	v_mfma_f32_16x16x32_bf16 v[102:105], v[174:177], v[190:193], v[102:105]
	v_mfma_f32_16x16x32_bf16 v[86:89], v[166:169], v[208:211], v[86:89]
	v_mfma_f32_16x16x32_bf16 v[82:85], v[174:177], v[208:211], v[82:85]
	v_mfma_f32_16x16x32_bf16 v[70:73], v[166:169], v[216:219], v[70:73]
	v_mfma_f32_16x16x32_bf16 v[66:69], v[174:177], v[216:219], v[66:69]
	s_setprio 0
	s_barrier
	s_add_i32 s54, s52, s6
	s_add_i32 m0, s54, 0xffffff80
	ds_read_b128 v[178:181], v145 offset:49152
	ds_read_b128 v[182:185], v145 offset:50176
	ds_read_b128 v[186:189], v145 offset:51200
	ds_read_b128 v[190:193], v145 offset:52224
	ds_read_b128 v[194:197], v145 offset:53248
	ds_read_b128 v[208:211], v145 offset:54272
	ds_read_b128 v[212:215], v145 offset:55296
	ds_read_b128 v[216:219], v145 offset:56320
	global_load_lds_dwordx4 v134, s[40:41] offset:128
	s_add_i32 m0, s54, 0x1f80
	s_nop 0
	global_load_lds_dwordx4 v94, s[40:41] offset:128
	s_add_i32 s54, s53, s6
	s_add_u32 s40, s40, 0x40080
	s_addc_u32 s41, s41, 0
	s_mov_b32 m0, s54
	s_nop 0
	global_load_lds_dwordx4 v134, s[40:41]
	s_add_i32 m0, s54, 0x2000
	s_nop 0
	global_load_lds_dwordx4 v94, s[40:41]
	s_add_u32 s42, s42, 0xfffc0080
	s_addc_u32 s43, s43, -1
	s_mov_b32 m0, s28
	s_nop 0
	global_load_lds_dwordx4 v134, s[42:43]
	s_mov_b32 m0, s29
	s_nop 0
	global_load_lds_dwordx4 v94, s[42:43]
	s_waitcnt vmcnt(8)
	s_waitcnt lgkmcnt(0)
	s_barrier
	s_setprio 1
	s_waitcnt lgkmcnt(0)
	v_mfma_f32_16x16x32_bf16 v[62:65], v[146:149], v[178:181], v[62:65]
	v_mfma_f32_16x16x32_bf16 v[58:61], v[154:157], v[178:181], v[58:61]
	v_mfma_f32_16x16x32_bf16 v[46:49], v[146:149], v[186:189], v[46:49]
	v_mfma_f32_16x16x32_bf16 v[42:45], v[154:157], v[186:189], v[42:45]
	v_mfma_f32_16x16x32_bf16 v[30:33], v[146:149], v[194:197], v[30:33]
	v_mfma_f32_16x16x32_bf16 v[26:29], v[154:157], v[194:197], v[26:29]
	v_mfma_f32_16x16x32_bf16 v[14:17], v[146:149], v[212:215], v[14:17]
	v_mfma_f32_16x16x32_bf16 v[10:13], v[154:157], v[212:215], v[10:13]
	v_mfma_f32_16x16x32_bf16 v[62:65], v[150:153], v[182:185], v[62:65]
	v_mfma_f32_16x16x32_bf16 v[58:61], v[158:161], v[182:185], v[58:61]
	v_mfma_f32_16x16x32_bf16 v[46:49], v[150:153], v[190:193], v[46:49]
	v_mfma_f32_16x16x32_bf16 v[42:45], v[158:161], v[190:193], v[42:45]
	v_mfma_f32_16x16x32_bf16 v[30:33], v[150:153], v[208:211], v[30:33]
	v_mfma_f32_16x16x32_bf16 v[26:29], v[158:161], v[208:211], v[26:29]
	v_mfma_f32_16x16x32_bf16 v[14:17], v[150:153], v[216:219], v[14:17]
	v_mfma_f32_16x16x32_bf16 v[10:13], v[158:161], v[216:219], v[10:13]
	s_setprio 0
	s_setprio 1
	v_mfma_f32_16x16x32_bf16 v[54:57], v[162:165], v[178:181], v[54:57]
	v_mfma_f32_16x16x32_bf16 v[50:53], v[170:173], v[178:181], v[50:53]
	v_mfma_f32_16x16x32_bf16 v[38:41], v[162:165], v[186:189], v[38:41]
	v_mfma_f32_16x16x32_bf16 v[34:37], v[170:173], v[186:189], v[34:37]
	v_mfma_f32_16x16x32_bf16 v[22:25], v[162:165], v[194:197], v[22:25]
	v_mfma_f32_16x16x32_bf16 v[18:21], v[170:173], v[194:197], v[18:21]
	v_mfma_f32_16x16x32_bf16 v[6:9], v[162:165], v[212:215], v[6:9]
	v_mfma_f32_16x16x32_bf16 v[2:5], v[170:173], v[212:215], v[2:5]
	v_mfma_f32_16x16x32_bf16 v[54:57], v[166:169], v[182:185], v[54:57]
	v_mfma_f32_16x16x32_bf16 v[50:53], v[174:177], v[182:185], v[50:53]
	v_mfma_f32_16x16x32_bf16 v[38:41], v[166:169], v[190:193], v[38:41]
	v_mfma_f32_16x16x32_bf16 v[34:37], v[174:177], v[190:193], v[34:37]
	v_mfma_f32_16x16x32_bf16 v[22:25], v[166:169], v[208:211], v[22:25]
	v_mfma_f32_16x16x32_bf16 v[18:21], v[174:177], v[208:211], v[18:21]
	v_mfma_f32_16x16x32_bf16 v[6:9], v[166:169], v[216:219], v[6:9]
	v_mfma_f32_16x16x32_bf16 v[2:5], v[174:177], v[216:219], v[2:5]
	s_setprio 0
	s_barrier
	s_add_i32 s51, s51, 2
	s_add_u32 s49, s49, 0x100
	s_addc_u32 s50, s50, 0
	s_add_u32 s38, s38, 0x100
	s_addc_u32 s39, s39, 0
.LBB0_565:
	s_add_u32 s40, s38, 0xfffc0080
	s_addc_u32 s41, s39, -1
	s_add_i32 s52, 0, 0x10000
	s_cmp_eq_u32 s51, 12
	s_cselect_b32 s43, s21, s41
	s_cselect_b32 s42, s47, s40
	s_cselect_b32 s41, s19, s50
	s_cselect_b32 s40, s48, s49
	s_add_i32 s54, 0, 0x14000
	ds_read_b128 v[146:149], v140
	ds_read_b128 v[150:153], v140 offset:1024
	ds_read_b128 v[154:157], v140 offset:2048
	ds_read_b128 v[158:161], v140 offset:3072
	ds_read_b128 v[162:165], v140 offset:16384
	ds_read_b128 v[166:169], v140 offset:17408
	ds_read_b128 v[170:173], v140 offset:18432
	ds_read_b128 v[174:177], v140 offset:19456
	s_add_i32 m0, s8, 0xc000
	ds_read_b128 v[178:181], v145
	ds_read_b128 v[182:185], v145 offset:1024
	ds_read_b128 v[186:189], v145 offset:2048
	ds_read_b128 v[190:193], v145 offset:3072
	ds_read_b128 v[194:197], v145 offset:4096
	ds_read_b128 v[208:211], v145 offset:5120
	ds_read_b128 v[212:215], v145 offset:6144
	ds_read_b128 v[216:219], v145 offset:7168
	global_load_lds_dwordx4 v138, s[38:39]
	s_add_i32 m0, s8, 0xe000
	s_nop 0
	global_load_lds_dwordx4 v136, s[38:39]
	s_waitcnt vmcnt(8)
	s_waitcnt lgkmcnt(0)
	s_barrier
	s_setprio 1
	s_waitcnt lgkmcnt(0)
	v_mfma_f32_16x16x32_bf16 v[130:133], v[146:149], v[178:181], v[130:133]
	v_mfma_f32_16x16x32_bf16 v[126:129], v[154:157], v[178:181], v[126:129]
	v_mfma_f32_16x16x32_bf16 v[114:117], v[146:149], v[186:189], v[114:117]
	v_mfma_f32_16x16x32_bf16 v[110:113], v[154:157], v[186:189], v[110:113]
	v_mfma_f32_16x16x32_bf16 v[98:101], v[146:149], v[194:197], v[98:101]
	v_mfma_f32_16x16x32_bf16 v[90:93], v[154:157], v[194:197], v[90:93]
	v_mfma_f32_16x16x32_bf16 v[78:81], v[146:149], v[212:215], v[78:81]
	v_mfma_f32_16x16x32_bf16 v[74:77], v[154:157], v[212:215], v[74:77]
	v_mfma_f32_16x16x32_bf16 v[130:133], v[150:153], v[182:185], v[130:133]
	v_mfma_f32_16x16x32_bf16 v[126:129], v[158:161], v[182:185], v[126:129]
	v_mfma_f32_16x16x32_bf16 v[114:117], v[150:153], v[190:193], v[114:117]
	v_mfma_f32_16x16x32_bf16 v[110:113], v[158:161], v[190:193], v[110:113]
	v_mfma_f32_16x16x32_bf16 v[98:101], v[150:153], v[208:211], v[98:101]
	v_mfma_f32_16x16x32_bf16 v[90:93], v[158:161], v[208:211], v[90:93]
	v_mfma_f32_16x16x32_bf16 v[78:81], v[150:153], v[216:219], v[78:81]
	v_mfma_f32_16x16x32_bf16 v[74:77], v[158:161], v[216:219], v[74:77]
	s_setprio 0
	s_setprio 1
	v_mfma_f32_16x16x32_bf16 v[122:125], v[162:165], v[178:181], v[122:125]
	v_mfma_f32_16x16x32_bf16 v[118:121], v[170:173], v[178:181], v[118:121]
	v_mfma_f32_16x16x32_bf16 v[106:109], v[162:165], v[186:189], v[106:109]
	v_mfma_f32_16x16x32_bf16 v[102:105], v[170:173], v[186:189], v[102:105]
	v_mfma_f32_16x16x32_bf16 v[86:89], v[162:165], v[194:197], v[86:89]
	v_mfma_f32_16x16x32_bf16 v[82:85], v[170:173], v[194:197], v[82:85]
	v_mfma_f32_16x16x32_bf16 v[70:73], v[162:165], v[212:215], v[70:73]
	v_mfma_f32_16x16x32_bf16 v[66:69], v[170:173], v[212:215], v[66:69]
	v_mfma_f32_16x16x32_bf16 v[122:125], v[166:169], v[182:185], v[122:125]
	v_mfma_f32_16x16x32_bf16 v[118:121], v[174:177], v[182:185], v[118:121]
	v_mfma_f32_16x16x32_bf16 v[106:109], v[166:169], v[190:193], v[106:109]
	v_mfma_f32_16x16x32_bf16 v[102:105], v[174:177], v[190:193], v[102:105]
	v_mfma_f32_16x16x32_bf16 v[86:89], v[166:169], v[208:211], v[86:89]
	v_mfma_f32_16x16x32_bf16 v[82:85], v[174:177], v[208:211], v[82:85]
	v_mfma_f32_16x16x32_bf16 v[70:73], v[166:169], v[216:219], v[70:73]
	v_mfma_f32_16x16x32_bf16 v[66:69], v[174:177], v[216:219], v[66:69]
	s_setprio 0
	s_barrier
	s_add_i32 s52, s52, s6
	s_mov_b32 m0, s52
	ds_read_b128 v[178:181], v145 offset:16384
	ds_read_b128 v[182:185], v145 offset:17408
	ds_read_b128 v[186:189], v145 offset:18432
	ds_read_b128 v[190:193], v145 offset:19456
	ds_read_b128 v[194:197], v145 offset:20480
	ds_read_b128 v[208:211], v145 offset:21504
	ds_read_b128 v[212:215], v145 offset:22528
	ds_read_b128 v[216:219], v145 offset:23552
	global_load_lds_dwordx4 v134, s[40:41]
	s_add_i32 m0, s52, 0x2000
	s_add_u32 s52, s40, 0x40000
	s_addc_u32 s53, s41, 0
	s_add_i32 s54, s54, s6
	global_load_lds_dwordx4 v94, s[40:41]
	s_mov_b32 m0, s54
	s_nop 0
	global_load_lds_dwordx4 v134, s[52:53]
	s_add_i32 m0, s54, 0x2000
	s_nop 0
	global_load_lds_dwordx4 v94, s[52:53]
	s_mov_b32 m0, s8
	s_nop 0
	global_load_lds_dwordx4 v134, s[42:43]
	s_mov_b32 m0, s9
	s_nop 0
	global_load_lds_dwordx4 v94, s[42:43]
	s_waitcnt vmcnt(8)
	s_waitcnt lgkmcnt(0)
	s_barrier
	s_setprio 1
	s_waitcnt lgkmcnt(0)
	v_mfma_f32_16x16x32_bf16 v[62:65], v[146:149], v[178:181], v[62:65]
	v_mfma_f32_16x16x32_bf16 v[58:61], v[154:157], v[178:181], v[58:61]
	v_mfma_f32_16x16x32_bf16 v[46:49], v[146:149], v[186:189], v[46:49]
	v_mfma_f32_16x16x32_bf16 v[42:45], v[154:157], v[186:189], v[42:45]
	v_mfma_f32_16x16x32_bf16 v[30:33], v[146:149], v[194:197], v[30:33]
	v_mfma_f32_16x16x32_bf16 v[26:29], v[154:157], v[194:197], v[26:29]
	v_mfma_f32_16x16x32_bf16 v[14:17], v[146:149], v[212:215], v[14:17]
	v_mfma_f32_16x16x32_bf16 v[10:13], v[154:157], v[212:215], v[10:13]
	v_mfma_f32_16x16x32_bf16 v[62:65], v[150:153], v[182:185], v[62:65]
	v_mfma_f32_16x16x32_bf16 v[58:61], v[158:161], v[182:185], v[58:61]
	v_mfma_f32_16x16x32_bf16 v[46:49], v[150:153], v[190:193], v[46:49]
	v_mfma_f32_16x16x32_bf16 v[42:45], v[158:161], v[190:193], v[42:45]
	v_mfma_f32_16x16x32_bf16 v[30:33], v[150:153], v[208:211], v[30:33]
	v_mfma_f32_16x16x32_bf16 v[26:29], v[158:161], v[208:211], v[26:29]
	v_mfma_f32_16x16x32_bf16 v[14:17], v[150:153], v[216:219], v[14:17]
	v_mfma_f32_16x16x32_bf16 v[10:13], v[158:161], v[216:219], v[10:13]
	s_setprio 0
	s_setprio 1
	v_mfma_f32_16x16x32_bf16 v[54:57], v[162:165], v[178:181], v[54:57]
	v_mfma_f32_16x16x32_bf16 v[50:53], v[170:173], v[178:181], v[50:53]
	v_mfma_f32_16x16x32_bf16 v[38:41], v[162:165], v[186:189], v[38:41]
	v_mfma_f32_16x16x32_bf16 v[34:37], v[170:173], v[186:189], v[34:37]
	v_mfma_f32_16x16x32_bf16 v[22:25], v[162:165], v[194:197], v[22:25]
	v_mfma_f32_16x16x32_bf16 v[18:21], v[170:173], v[194:197], v[18:21]
	v_mfma_f32_16x16x32_bf16 v[6:9], v[162:165], v[212:215], v[6:9]
	v_mfma_f32_16x16x32_bf16 v[2:5], v[170:173], v[212:215], v[2:5]
	v_mfma_f32_16x16x32_bf16 v[54:57], v[166:169], v[182:185], v[54:57]
	v_mfma_f32_16x16x32_bf16 v[50:53], v[174:177], v[182:185], v[50:53]
	v_mfma_f32_16x16x32_bf16 v[38:41], v[166:169], v[190:193], v[38:41]
	v_mfma_f32_16x16x32_bf16 v[34:37], v[174:177], v[190:193], v[34:37]
	v_mfma_f32_16x16x32_bf16 v[22:25], v[166:169], v[208:211], v[22:25]
	v_mfma_f32_16x16x32_bf16 v[18:21], v[174:177], v[208:211], v[18:21]
	v_mfma_f32_16x16x32_bf16 v[6:9], v[166:169], v[216:219], v[6:9]
	v_mfma_f32_16x16x32_bf16 v[2:5], v[174:177], v[216:219], v[2:5]
	s_setprio 0
	s_barrier
	s_add_i32 s52, 0, 0x18000
	s_add_i32 s53, 0, 0x1c000
	ds_read_b128 v[146:149], v140 offset:32768
	ds_read_b128 v[150:153], v140 offset:33792
	ds_read_b128 v[154:157], v140 offset:34816
	ds_read_b128 v[158:161], v140 offset:35840
	ds_read_b128 v[162:165], v140 offset:49152
	ds_read_b128 v[166:169], v140 offset:50176
	ds_read_b128 v[170:173], v140 offset:51200
	ds_read_b128 v[174:177], v140 offset:52224
	s_add_u32 s42, s42, 0x40000
	s_addc_u32 s43, s43, 0
	s_mov_b32 m0, s12
	ds_read_b128 v[178:181], v145 offset:32768
	ds_read_b128 v[182:185], v145 offset:33792
	ds_read_b128 v[186:189], v145 offset:34816
	ds_read_b128 v[190:193], v145 offset:35840
	ds_read_b128 v[194:197], v145 offset:36864
	ds_read_b128 v[208:211], v145 offset:37888
	ds_read_b128 v[212:215], v145 offset:38912
	ds_read_b128 v[216:219], v145 offset:39936
	global_load_lds_dwordx4 v134, s[42:43]
	s_mov_b32 m0, s13
	s_nop 0
	global_load_lds_dwordx4 v94, s[42:43]
	s_waitcnt vmcnt(8)
	s_waitcnt lgkmcnt(0)
	s_barrier
	s_setprio 1
	s_waitcnt lgkmcnt(0)
	v_mfma_f32_16x16x32_bf16 v[130:133], v[146:149], v[178:181], v[130:133]
	v_mfma_f32_16x16x32_bf16 v[126:129], v[154:157], v[178:181], v[126:129]
	v_mfma_f32_16x16x32_bf16 v[114:117], v[146:149], v[186:189], v[114:117]
	v_mfma_f32_16x16x32_bf16 v[110:113], v[154:157], v[186:189], v[110:113]
	v_mfma_f32_16x16x32_bf16 v[98:101], v[146:149], v[194:197], v[98:101]
	v_mfma_f32_16x16x32_bf16 v[90:93], v[154:157], v[194:197], v[90:93]
	v_mfma_f32_16x16x32_bf16 v[78:81], v[146:149], v[212:215], v[78:81]
	v_mfma_f32_16x16x32_bf16 v[74:77], v[154:157], v[212:215], v[74:77]
	v_mfma_f32_16x16x32_bf16 v[130:133], v[150:153], v[182:185], v[130:133]
	v_mfma_f32_16x16x32_bf16 v[126:129], v[158:161], v[182:185], v[126:129]
	v_mfma_f32_16x16x32_bf16 v[114:117], v[150:153], v[190:193], v[114:117]
	v_mfma_f32_16x16x32_bf16 v[110:113], v[158:161], v[190:193], v[110:113]
	v_mfma_f32_16x16x32_bf16 v[98:101], v[150:153], v[208:211], v[98:101]
	v_mfma_f32_16x16x32_bf16 v[90:93], v[158:161], v[208:211], v[90:93]
	v_mfma_f32_16x16x32_bf16 v[78:81], v[150:153], v[216:219], v[78:81]
	v_mfma_f32_16x16x32_bf16 v[74:77], v[158:161], v[216:219], v[74:77]
	s_setprio 0
	s_setprio 1
	v_mfma_f32_16x16x32_bf16 v[122:125], v[162:165], v[178:181], v[122:125]
	v_mfma_f32_16x16x32_bf16 v[118:121], v[170:173], v[178:181], v[118:121]
	v_mfma_f32_16x16x32_bf16 v[106:109], v[162:165], v[186:189], v[106:109]
	v_mfma_f32_16x16x32_bf16 v[102:105], v[170:173], v[186:189], v[102:105]
	v_mfma_f32_16x16x32_bf16 v[86:89], v[162:165], v[194:197], v[86:89]
	v_mfma_f32_16x16x32_bf16 v[82:85], v[170:173], v[194:197], v[82:85]
	v_mfma_f32_16x16x32_bf16 v[70:73], v[162:165], v[212:215], v[70:73]
	v_mfma_f32_16x16x32_bf16 v[66:69], v[170:173], v[212:215], v[66:69]
	v_mfma_f32_16x16x32_bf16 v[122:125], v[166:169], v[182:185], v[122:125]
	v_mfma_f32_16x16x32_bf16 v[118:121], v[174:177], v[182:185], v[118:121]
	v_mfma_f32_16x16x32_bf16 v[106:109], v[166:169], v[190:193], v[106:109]
	v_mfma_f32_16x16x32_bf16 v[102:105], v[174:177], v[190:193], v[102:105]
	v_mfma_f32_16x16x32_bf16 v[86:89], v[166:169], v[208:211], v[86:89]
	v_mfma_f32_16x16x32_bf16 v[82:85], v[174:177], v[208:211], v[82:85]
	v_mfma_f32_16x16x32_bf16 v[70:73], v[166:169], v[216:219], v[70:73]
	v_mfma_f32_16x16x32_bf16 v[66:69], v[174:177], v[216:219], v[66:69]
	s_setprio 0
	s_barrier
	s_add_i32 s54, s52, s6
	s_add_i32 m0, s54, 0xffffff80
	ds_read_b128 v[178:181], v145 offset:49152
	ds_read_b128 v[182:185], v145 offset:50176
	ds_read_b128 v[186:189], v145 offset:51200
	ds_read_b128 v[190:193], v145 offset:52224
	ds_read_b128 v[194:197], v145 offset:53248
	ds_read_b128 v[208:211], v145 offset:54272
	ds_read_b128 v[212:215], v145 offset:55296
	ds_read_b128 v[216:219], v145 offset:56320
	global_load_lds_dwordx4 v134, s[40:41] offset:128
	s_add_i32 m0, s54, 0x1f80
	s_nop 0
	global_load_lds_dwordx4 v94, s[40:41] offset:128
	s_add_i32 s54, s53, s6
	s_add_u32 s40, s40, 0x40080
	s_addc_u32 s41, s41, 0
	s_mov_b32 m0, s54
	s_nop 0
	global_load_lds_dwordx4 v134, s[40:41]
	s_add_i32 m0, s54, 0x2000
	s_nop 0
	global_load_lds_dwordx4 v94, s[40:41]
	s_add_u32 s42, s42, 0xfffc0080
	s_addc_u32 s43, s43, -1
	s_mov_b32 m0, s28
	s_nop 0
	global_load_lds_dwordx4 v134, s[42:43]
	s_mov_b32 m0, s29
	s_nop 0
	global_load_lds_dwordx4 v94, s[42:43]
	s_waitcnt vmcnt(8)
	s_waitcnt lgkmcnt(0)
	s_cmp_lg_u32 s51, 12
	s_cbranch_scc1 .Lup_nopf
	s_lshl_b32 s54, s46, 8
	s_add_i32 s54, s54, s25
	v_and_b32_e32 v232, 0x18, v143
	v_or_b32_e32 v233, s54, v97
	v_lshrrev_b32_e32 v232, 1, v232
	v_lshl_add_u32 v232, v233, 4, v232
	global_load_dword v233, v232, s[16:17]
	global_load_dword v234, v232, s[16:17] offset:256
	global_load_dword v235, v232, s[16:17] offset:512
	global_load_dword v236, v232, s[16:17] offset:768
	global_load_dword v237, v232, s[16:17] offset:2048
	global_load_dword v238, v232, s[16:17] offset:2304
	global_load_dword v239, v232, s[16:17] offset:2560
	global_load_dword v240, v232, s[16:17] offset:2816
